# v46 + P0 plain conversion tiles split 12/28 between blocks with two / one ada-projection jobs
# baseline (speedup 1.0000x reference)
.Lwf_plain:
	v_and_b32_e32 v29, 63, v155
	v_lshrrev_b32_e32 v24, 6, v155
	v_lshlrev_b32_e32 v26, 2, v29
	v_lshlrev_b32_e32 v29, 1, v29
	v_readfirstlane_b32 s58, v24
	s_load_dword s6, s[0:1], 0x4c8
	s_waitcnt lgkmcnt(0)
	s_lshl_b32 s58, s58, 4
	s_cmpk_lg_u32 s6, 0x100
	s_cbranch_scc1 .Lwf_generic
	s_mov_b32 s6, 0
	s_add_i32 s7, s89, 0xfffffe80
	s_mov_b32 s30, 2
	s_cmpk_ge_i32 s7, 0x300
	s_cselect_b32 s30, 3, s30
	s_cmpk_ge_i32 s7, 0x500
	s_cselect_b32 s30, 4, s30
	s_cmpk_ge_i32 s7, 0x700
	s_cselect_b32 s30, 5, s30
	s_cmpk_ge_i32 s7, 0x900
	s_cselect_b32 s30, 6, s30
	s_cmpk_ge_i32 s7, 0xb00
	s_cselect_b32 s30, 7, s30
	s_cmpk_ge_i32 s7, 0xd00
	s_cselect_b32 s30, 8, s30
	s_cmpk_ge_i32 s7, 0xf00
	s_cselect_b32 s30, 9, s30
	s_cmpk_ge_i32 s7, 0x1100
	s_cselect_b32 s30, 10, s30
	s_cmpk_ge_i32 s7, 0x1280
	s_cselect_b32 s30, 11, s30
	s_cmpk_ge_i32 s7, 0x1400
	s_cselect_b32 s30, 12, s30
	s_cmpk_ge_i32 s7, 0x1480
	s_cselect_b32 s30, 13, s30
	s_mul_i32 s59, s30, 48
	s_add_u32 s10, s0, s59
	s_addc_u32 s11, s1, 0
	s_load_dwordx2 s[50:51], s[10:11], 0x100
	s_load_dwordx2 s[52:53], s[10:11], 0x110
	s_load_dwordx2 s[90:91], s[10:11], 0x118
	s_load_dword s30, s[10:11], 0x128
	s_load_dwordx2 vcc, s[0:1], 0xf8
	s_waitcnt lgkmcnt(0)
	s_sub_i32 s7, s7, s30
	s_lshr_b32 s59, s90, 7
	s_add_i32 s10, s59, -1
	s_and_b32 s10, s7, s10
	s_ff1_i32_b32 s59, s59
	s_lshr_b32 s7, s7, s59
	s_lshl_b32 s10, s10, 7
	s_add_i32 s10, s10, s58
	s_lshl_b32 s11, s7, 6
	s_mul_i32 s59, s10, s91
	s_add_i32 s59, s59, s11
	s_lshl_b32 s59, s59, 2
	s_add_u32 s50, s50, s59
	s_addc_u32 s51, s51, 0
	s_mul_i32 s59, s11, s90
	s_add_i32 s59, s59, s10
	s_lshl_b32 s59, s59, 1
	s_add_u32 s52, s52, s59
	s_addc_u32 s53, s53, 0
	s_add_u32 s52, s52, vcc_lo
	s_addc_u32 s53, s53, vcc_hi
	v_mul_u32_u24_e32 v27, s90, v29
	s_lshl_b32 s91, s91, 2
	global_load_dword v0, v26, s[50:51] nt
	s_add_u32 s50, s50, s91
	s_addc_u32 s51, s51, 0
	global_load_dword v1, v26, s[50:51] nt
	s_add_u32 s50, s50, s91
	s_addc_u32 s51, s51, 0
	global_load_dword v2, v26, s[50:51] nt
	s_add_u32 s50, s50, s91
	s_addc_u32 s51, s51, 0
	global_load_dword v3, v26, s[50:51] nt
	s_add_u32 s50, s50, s91
	s_addc_u32 s51, s51, 0
	global_load_dword v4, v26, s[50:51] nt
	s_add_u32 s50, s50, s91
	s_addc_u32 s51, s51, 0
	global_load_dword v5, v26, s[50:51] nt
	s_add_u32 s50, s50, s91
	s_addc_u32 s51, s51, 0
	global_load_dword v6, v26, s[50:51] nt
	s_add_u32 s50, s50, s91
	s_addc_u32 s51, s51, 0
	global_load_dword v7, v26, s[50:51] nt
	s_add_u32 s50, s50, s91
	s_addc_u32 s51, s51, 0
	global_load_dword v8, v26, s[50:51] nt
	s_add_u32 s50, s50, s91
	s_addc_u32 s51, s51, 0
	global_load_dword v9, v26, s[50:51] nt
	s_add_u32 s50, s50, s91
	s_addc_u32 s51, s51, 0
	global_load_dword v10, v26, s[50:51] nt
	s_add_u32 s50, s50, s91
	s_addc_u32 s51, s51, 0
	global_load_dword v11, v26, s[50:51] nt
	s_add_u32 s50, s50, s91
	s_addc_u32 s51, s51, 0
	global_load_dword v12, v26, s[50:51] nt
	s_add_u32 s50, s50, s91
	s_addc_u32 s51, s51, 0
	global_load_dword v13, v26, s[50:51] nt
	s_add_u32 s50, s50, s91
	s_addc_u32 s51, s51, 0
	global_load_dword v14, v26, s[50:51] nt
	s_add_u32 s50, s50, s91
	s_addc_u32 s51, s51, 0
	global_load_dword v15, v26, s[50:51] nt
	s_add_i32 s6, s6, 1
	s_cmp_ge_u32 s92, 0x80
	s_cselect_b32 s7, 28, 12
	s_cmp_ge_u32 s6, s7
	s_cbranch_scc1 .Lwf_pdrain1
	s_add_i32 s7, s92, 0x80
	s_and_b32 s7, s7, 0xff
	s_lshl_b32 s89, s6, 8
	s_add_i32 s89, s89, s7
	s_addk_i32 s89, 0x280
	s_lshl_b32 s7, s6, 7
	s_add_i32 s7, s7, s92
	s_addk_i32 s7, 0x800
	s_cmp_ge_u32 s6, 12
	s_cselect_b32 s89, s7, s89
	s_add_i32 s7, s89, 0xfffffe80
	s_mov_b32 s30, 2
	s_cmpk_ge_i32 s7, 0x300
	s_cselect_b32 s30, 3, s30
	s_cmpk_ge_i32 s7, 0x500
	s_cselect_b32 s30, 4, s30
	s_cmpk_ge_i32 s7, 0x700
	s_cselect_b32 s30, 5, s30
	s_cmpk_ge_i32 s7, 0x900
	s_cselect_b32 s30, 6, s30
	s_cmpk_ge_i32 s7, 0xb00
	s_cselect_b32 s30, 7, s30
	s_cmpk_ge_i32 s7, 0xd00
	s_cselect_b32 s30, 8, s30
	s_cmpk_ge_i32 s7, 0xf00
	s_cselect_b32 s30, 9, s30
	s_cmpk_ge_i32 s7, 0x1100
	s_cselect_b32 s30, 10, s30
	s_cmpk_ge_i32 s7, 0x1280
	s_cselect_b32 s30, 11, s30
	s_cmpk_ge_i32 s7, 0x1400
	s_cselect_b32 s30, 12, s30
	s_cmpk_ge_i32 s7, 0x1480
	s_cselect_b32 s30, 13, s30
	s_mul_i32 s59, s30, 48
	s_add_u32 s10, s0, s59
	s_addc_u32 s11, s1, 0
	s_load_dwordx2 s[50:51], s[10:11], 0x100
	s_load_dwordx2 s[54:55], s[10:11], 0x110
	s_load_dwordx2 s[90:91], s[10:11], 0x118
	s_load_dword s30, s[10:11], 0x128
	s_load_dwordx2 vcc, s[0:1], 0xf8
	s_waitcnt lgkmcnt(0)
	s_sub_i32 s7, s7, s30
	s_lshr_b32 s59, s90, 7
	s_add_i32 s10, s59, -1
	s_and_b32 s10, s7, s10
	s_ff1_i32_b32 s59, s59
	s_lshr_b32 s7, s7, s59
	s_lshl_b32 s10, s10, 7
	s_add_i32 s10, s10, s58
	s_lshl_b32 s11, s7, 6
	s_mul_i32 s59, s10, s91
	s_add_i32 s59, s59, s11
	s_lshl_b32 s59, s59, 2
	s_add_u32 s50, s50, s59
	s_addc_u32 s51, s51, 0
	s_mul_i32 s59, s11, s90
	s_add_i32 s59, s59, s10
	s_lshl_b32 s59, s59, 1
	s_add_u32 s54, s54, s59
	s_addc_u32 s55, s55, 0
	s_add_u32 s54, s54, vcc_lo
	s_addc_u32 s55, s55, vcc_hi
	v_mul_u32_u24_e32 v28, s90, v29
	s_lshl_b32 s91, s91, 2
	global_load_dword v30, v26, s[50:51] nt
	s_add_u32 s50, s50, s91
	s_addc_u32 s51, s51, 0
	global_load_dword v31, v26, s[50:51] nt
	s_add_u32 s50, s50, s91
	s_addc_u32 s51, s51, 0
	global_load_dword v32, v26, s[50:51] nt
	s_add_u32 s50, s50, s91
	s_addc_u32 s51, s51, 0
	global_load_dword v33, v26, s[50:51] nt
	s_add_u32 s50, s50, s91
	s_addc_u32 s51, s51, 0
	global_load_dword v34, v26, s[50:51] nt
	s_add_u32 s50, s50, s91
	s_addc_u32 s51, s51, 0
	global_load_dword v35, v26, s[50:51] nt
	s_add_u32 s50, s50, s91
	s_addc_u32 s51, s51, 0
	global_load_dword v36, v26, s[50:51] nt
	s_add_u32 s50, s50, s91
	s_addc_u32 s51, s51, 0
	global_load_dword v37, v26, s[50:51] nt
	s_add_u32 s50, s50, s91
	s_addc_u32 s51, s51, 0
	global_load_dword v38, v26, s[50:51] nt
	s_add_u32 s50, s50, s91
	s_addc_u32 s51, s51, 0
	global_load_dword v39, v26, s[50:51] nt
	s_add_u32 s50, s50, s91
	s_addc_u32 s51, s51, 0
	global_load_dword v40, v26, s[50:51] nt
	s_add_u32 s50, s50, s91
	s_addc_u32 s51, s51, 0
	global_load_dword v41, v26, s[50:51] nt
	s_add_u32 s50, s50, s91
	s_addc_u32 s51, s51, 0
	global_load_dword v42, v26, s[50:51] nt
	s_add_u32 s50, s50, s91
	s_addc_u32 s51, s51, 0
	global_load_dword v43, v26, s[50:51] nt
	s_add_u32 s50, s50, s91
	s_addc_u32 s51, s51, 0
	global_load_dword v44, v26, s[50:51] nt
	s_add_u32 s50, s50, s91
	s_addc_u32 s51, s51, 0
	global_load_dword v45, v26, s[50:51] nt
	s_add_i32 s6, s6, 1
	s_cmp_ge_u32 s92, 0x80
	s_cselect_b32 s7, 28, 12
	s_cmp_ge_u32 s6, s7
	s_cbranch_scc1 .Lwf_pdrain2
	s_add_i32 s7, s92, 0x80
	s_and_b32 s7, s7, 0xff
	s_lshl_b32 s89, s6, 8
	s_add_i32 s89, s89, s7
	s_addk_i32 s89, 0x280
	s_lshl_b32 s7, s6, 7
	s_add_i32 s7, s7, s92
	s_addk_i32 s7, 0x800
	s_cmp_ge_u32 s6, 12
	s_cselect_b32 s89, s7, s89
	s_add_i32 s7, s89, 0xfffffe80
	s_mov_b32 s30, 2
	s_cmpk_ge_i32 s7, 0x300
	s_cselect_b32 s30, 3, s30
	s_cmpk_ge_i32 s7, 0x500
	s_cselect_b32 s30, 4, s30
	s_cmpk_ge_i32 s7, 0x700
	s_cselect_b32 s30, 5, s30
	s_cmpk_ge_i32 s7, 0x900
	s_cselect_b32 s30, 6, s30
	s_cmpk_ge_i32 s7, 0xb00
	s_cselect_b32 s30, 7, s30
	s_cmpk_ge_i32 s7, 0xd00
	s_cselect_b32 s30, 8, s30
	s_cmpk_ge_i32 s7, 0xf00
	s_cselect_b32 s30, 9, s30
	s_cmpk_ge_i32 s7, 0x1100
	s_cselect_b32 s30, 10, s30
	s_cmpk_ge_i32 s7, 0x1280
	s_cselect_b32 s30, 11, s30
	s_cmpk_ge_i32 s7, 0x1400
	s_cselect_b32 s30, 12, s30
	s_cmpk_ge_i32 s7, 0x1480
	s_cselect_b32 s30, 13, s30
	s_mul_i32 s59, s30, 48
	s_add_u32 s10, s0, s59
	s_addc_u32 s11, s1, 0
	s_load_dwordx2 s[50:51], s[10:11], 0x100
	s_load_dwordx2 s[56:57], s[10:11], 0x110
	s_load_dwordx2 s[90:91], s[10:11], 0x118
	s_load_dword s30, s[10:11], 0x128
	s_load_dwordx2 vcc, s[0:1], 0xf8
	s_waitcnt lgkmcnt(0)
	s_sub_i32 s7, s7, s30
	s_lshr_b32 s59, s90, 7
	s_add_i32 s10, s59, -1
	s_and_b32 s10, s7, s10
	s_ff1_i32_b32 s59, s59
	s_lshr_b32 s7, s7, s59
	s_lshl_b32 s10, s10, 7
	s_add_i32 s10, s10, s58
	s_lshl_b32 s11, s7, 6
	s_mul_i32 s59, s10, s91
	s_add_i32 s59, s59, s11
	s_lshl_b32 s59, s59, 2
	s_add_u32 s50, s50, s59
	s_addc_u32 s51, s51, 0
	s_mul_i32 s59, s11, s90
	s_add_i32 s59, s59, s10
	s_lshl_b32 s59, s59, 1
	s_add_u32 s56, s56, s59
	s_addc_u32 s57, s57, 0
	s_add_u32 s56, s56, vcc_lo
	s_addc_u32 s57, s57, vcc_hi
	v_mul_u32_u24_e32 v78, s90, v29
	s_lshl_b32 s91, s91, 2
	global_load_dword v46, v26, s[50:51] nt
	s_add_u32 s50, s50, s91
	s_addc_u32 s51, s51, 0
	global_load_dword v47, v26, s[50:51] nt
	s_add_u32 s50, s50, s91
	s_addc_u32 s51, s51, 0
	global_load_dword v48, v26, s[50:51] nt
	s_add_u32 s50, s50, s91
	s_addc_u32 s51, s51, 0
	global_load_dword v49, v26, s[50:51] nt
	s_add_u32 s50, s50, s91
	s_addc_u32 s51, s51, 0
	global_load_dword v50, v26, s[50:51] nt
	s_add_u32 s50, s50, s91
	s_addc_u32 s51, s51, 0
	global_load_dword v51, v26, s[50:51] nt
	s_add_u32 s50, s50, s91
	s_addc_u32 s51, s51, 0
	global_load_dword v52, v26, s[50:51] nt
	s_add_u32 s50, s50, s91
	s_addc_u32 s51, s51, 0
	global_load_dword v53, v26, s[50:51] nt
	s_add_u32 s50, s50, s91
	s_addc_u32 s51, s51, 0
	global_load_dword v54, v26, s[50:51] nt
	s_add_u32 s50, s50, s91
	s_addc_u32 s51, s51, 0
	global_load_dword v55, v26, s[50:51] nt
	s_add_u32 s50, s50, s91
	s_addc_u32 s51, s51, 0
	global_load_dword v56, v26, s[50:51] nt
	s_add_u32 s50, s50, s91
	s_addc_u32 s51, s51, 0
	global_load_dword v57, v26, s[50:51] nt
	s_add_u32 s50, s50, s91
	s_addc_u32 s51, s51, 0
	global_load_dword v58, v26, s[50:51] nt
	s_add_u32 s50, s50, s91
	s_addc_u32 s51, s51, 0
	global_load_dword v59, v26, s[50:51] nt
	s_add_u32 s50, s50, s91
	s_addc_u32 s51, s51, 0
	global_load_dword v60, v26, s[50:51] nt
	s_add_u32 s50, s50, s91
	s_addc_u32 s51, s51, 0
	global_load_dword v61, v26, s[50:51] nt
.Lwf_loop:
	s_waitcnt vmcnt(32)
	v_cvt_pk_bf16_f32 v0, v0, v1
	v_cvt_pk_bf16_f32 v1, v2, v3
	v_cvt_pk_bf16_f32 v2, v4, v5
	v_cvt_pk_bf16_f32 v3, v6, v7
	v_cvt_pk_bf16_f32 v4, v8, v9
	v_cvt_pk_bf16_f32 v5, v10, v11
	v_cvt_pk_bf16_f32 v6, v12, v13
	v_cvt_pk_bf16_f32 v7, v14, v15
	global_store_dwordx4 v27, v[0:3], s[52:53]
	global_store_dwordx4 v27, v[4:7], s[52:53] offset:16
	s_add_i32 s6, s6, 1
	s_cmp_ge_u32 s92, 0x80
	s_cselect_b32 s7, 28, 12
	s_cmp_ge_u32 s6, s7
	s_cbranch_scc1 .Lwf_drain0
	s_add_i32 s7, s92, 0x80
	s_and_b32 s7, s7, 0xff
	s_lshl_b32 s89, s6, 8
	s_add_i32 s89, s89, s7
	s_addk_i32 s89, 0x280
	s_lshl_b32 s7, s6, 7
	s_add_i32 s7, s7, s92
	s_addk_i32 s7, 0x800
	s_cmp_ge_u32 s6, 12
	s_cselect_b32 s89, s7, s89
	s_add_i32 s7, s89, 0xfffffe80
	s_mov_b32 s30, 2
	s_cmpk_ge_i32 s7, 0x300
	s_cselect_b32 s30, 3, s30
	s_cmpk_ge_i32 s7, 0x500
	s_cselect_b32 s30, 4, s30
	s_cmpk_ge_i32 s7, 0x700
	s_cselect_b32 s30, 5, s30
	s_cmpk_ge_i32 s7, 0x900
	s_cselect_b32 s30, 6, s30
	s_cmpk_ge_i32 s7, 0xb00
	s_cselect_b32 s30, 7, s30
	s_cmpk_ge_i32 s7, 0xd00
	s_cselect_b32 s30, 8, s30
	s_cmpk_ge_i32 s7, 0xf00
	s_cselect_b32 s30, 9, s30
	s_cmpk_ge_i32 s7, 0x1100
	s_cselect_b32 s30, 10, s30
	s_cmpk_ge_i32 s7, 0x1280
	s_cselect_b32 s30, 11, s30
	s_cmpk_ge_i32 s7, 0x1400
	s_cselect_b32 s30, 12, s30
	s_cmpk_ge_i32 s7, 0x1480
	s_cselect_b32 s30, 13, s30
	s_mul_i32 s59, s30, 48
	s_add_u32 s10, s0, s59
	s_addc_u32 s11, s1, 0
	s_load_dwordx2 s[50:51], s[10:11], 0x100
	s_load_dwordx2 s[52:53], s[10:11], 0x110
	s_load_dwordx2 s[90:91], s[10:11], 0x118
	s_load_dword s30, s[10:11], 0x128
	s_load_dwordx2 vcc, s[0:1], 0xf8
	s_waitcnt lgkmcnt(0)
	s_sub_i32 s7, s7, s30
	s_lshr_b32 s59, s90, 7
	s_add_i32 s10, s59, -1
	s_and_b32 s10, s7, s10
	s_ff1_i32_b32 s59, s59
	s_lshr_b32 s7, s7, s59
	s_lshl_b32 s10, s10, 7
	s_add_i32 s10, s10, s58
	s_lshl_b32 s11, s7, 6
	s_mul_i32 s59, s10, s91
	s_add_i32 s59, s59, s11
	s_lshl_b32 s59, s59, 2
	s_add_u32 s50, s50, s59
	s_addc_u32 s51, s51, 0
	s_mul_i32 s59, s11, s90
	s_add_i32 s59, s59, s10
	s_lshl_b32 s59, s59, 1
	s_add_u32 s52, s52, s59
	s_addc_u32 s53, s53, 0
	s_add_u32 s52, s52, vcc_lo
	s_addc_u32 s53, s53, vcc_hi
	v_mul_u32_u24_e32 v27, s90, v29
	s_lshl_b32 s91, s91, 2
	global_load_dword v0, v26, s[50:51] nt
	s_add_u32 s50, s50, s91
	s_addc_u32 s51, s51, 0
	global_load_dword v1, v26, s[50:51] nt
	s_add_u32 s50, s50, s91
	s_addc_u32 s51, s51, 0
	global_load_dword v2, v26, s[50:51] nt
	s_add_u32 s50, s50, s91
	s_addc_u32 s51, s51, 0
	global_load_dword v3, v26, s[50:51] nt
	s_add_u32 s50, s50, s91
	s_addc_u32 s51, s51, 0
	global_load_dword v4, v26, s[50:51] nt
	s_add_u32 s50, s50, s91
	s_addc_u32 s51, s51, 0
	global_load_dword v5, v26, s[50:51] nt
	s_add_u32 s50, s50, s91
	s_addc_u32 s51, s51, 0
	global_load_dword v6, v26, s[50:51] nt
	s_add_u32 s50, s50, s91
	s_addc_u32 s51, s51, 0
	global_load_dword v7, v26, s[50:51] nt
	s_add_u32 s50, s50, s91
	s_addc_u32 s51, s51, 0
	global_load_dword v8, v26, s[50:51] nt
	s_add_u32 s50, s50, s91
	s_addc_u32 s51, s51, 0
	global_load_dword v9, v26, s[50:51] nt
	s_add_u32 s50, s50, s91
	s_addc_u32 s51, s51, 0
	global_load_dword v10, v26, s[50:51] nt
	s_add_u32 s50, s50, s91
	s_addc_u32 s51, s51, 0
	global_load_dword v11, v26, s[50:51] nt
	s_add_u32 s50, s50, s91
	s_addc_u32 s51, s51, 0
	global_load_dword v12, v26, s[50:51] nt
	s_add_u32 s50, s50, s91
	s_addc_u32 s51, s51, 0
	global_load_dword v13, v26, s[50:51] nt
	s_add_u32 s50, s50, s91
	s_addc_u32 s51, s51, 0
	global_load_dword v14, v26, s[50:51] nt
	s_add_u32 s50, s50, s91
	s_addc_u32 s51, s51, 0
	global_load_dword v15, v26, s[50:51] nt
	s_waitcnt vmcnt(32)
	v_cvt_pk_bf16_f32 v30, v30, v31
	v_cvt_pk_bf16_f32 v31, v32, v33
	v_cvt_pk_bf16_f32 v32, v34, v35
	v_cvt_pk_bf16_f32 v33, v36, v37
	v_cvt_pk_bf16_f32 v34, v38, v39
	v_cvt_pk_bf16_f32 v35, v40, v41
	v_cvt_pk_bf16_f32 v36, v42, v43
	v_cvt_pk_bf16_f32 v37, v44, v45
	global_store_dwordx4 v28, v[30:33], s[54:55]
	global_store_dwordx4 v28, v[34:37], s[54:55] offset:16
	s_add_i32 s6, s6, 1
	s_cmp_ge_u32 s92, 0x80
	s_cselect_b32 s7, 28, 12
	s_cmp_ge_u32 s6, s7
	s_cbranch_scc1 .Lwf_drain1
	s_add_i32 s7, s92, 0x80
	s_and_b32 s7, s7, 0xff
	s_lshl_b32 s89, s6, 8
	s_add_i32 s89, s89, s7
	s_addk_i32 s89, 0x280
	s_lshl_b32 s7, s6, 7
	s_add_i32 s7, s7, s92
	s_addk_i32 s7, 0x800
	s_cmp_ge_u32 s6, 12
	s_cselect_b32 s89, s7, s89
	s_add_i32 s7, s89, 0xfffffe80
	s_mov_b32 s30, 2
	s_cmpk_ge_i32 s7, 0x300
	s_cselect_b32 s30, 3, s30
	s_cmpk_ge_i32 s7, 0x500
	s_cselect_b32 s30, 4, s30
	s_cmpk_ge_i32 s7, 0x700
	s_cselect_b32 s30, 5, s30
	s_cmpk_ge_i32 s7, 0x900
	s_cselect_b32 s30, 6, s30
	s_cmpk_ge_i32 s7, 0xb00
	s_cselect_b32 s30, 7, s30
	s_cmpk_ge_i32 s7, 0xd00
	s_cselect_b32 s30, 8, s30
	s_cmpk_ge_i32 s7, 0xf00
	s_cselect_b32 s30, 9, s30
	s_cmpk_ge_i32 s7, 0x1100
	s_cselect_b32 s30, 10, s30
	s_cmpk_ge_i32 s7, 0x1280
	s_cselect_b32 s30, 11, s30
	s_cmpk_ge_i32 s7, 0x1400
	s_cselect_b32 s30, 12, s30
	s_cmpk_ge_i32 s7, 0x1480
	s_cselect_b32 s30, 13, s30
	s_mul_i32 s59, s30, 48
	s_add_u32 s10, s0, s59
	s_addc_u32 s11, s1, 0
	s_load_dwordx2 s[50:51], s[10:11], 0x100
	s_load_dwordx2 s[54:55], s[10:11], 0x110
	s_load_dwordx2 s[90:91], s[10:11], 0x118
	s_load_dword s30, s[10:11], 0x128
	s_load_dwordx2 vcc, s[0:1], 0xf8
	s_waitcnt lgkmcnt(0)
	s_sub_i32 s7, s7, s30
	s_lshr_b32 s59, s90, 7
	s_add_i32 s10, s59, -1
	s_and_b32 s10, s7, s10
	s_ff1_i32_b32 s59, s59
	s_lshr_b32 s7, s7, s59
	s_lshl_b32 s10, s10, 7
	s_add_i32 s10, s10, s58
	s_lshl_b32 s11, s7, 6
	s_mul_i32 s59, s10, s91
	s_add_i32 s59, s59, s11
	s_lshl_b32 s59, s59, 2
	s_add_u32 s50, s50, s59
	s_addc_u32 s51, s51, 0
	s_mul_i32 s59, s11, s90
	s_add_i32 s59, s59, s10
	s_lshl_b32 s59, s59, 1
	s_add_u32 s54, s54, s59
	s_addc_u32 s55, s55, 0
	s_add_u32 s54, s54, vcc_lo
	s_addc_u32 s55, s55, vcc_hi
	v_mul_u32_u24_e32 v28, s90, v29
	s_lshl_b32 s91, s91, 2
	global_load_dword v30, v26, s[50:51] nt
	s_add_u32 s50, s50, s91
	s_addc_u32 s51, s51, 0
	global_load_dword v31, v26, s[50:51] nt
	s_add_u32 s50, s50, s91
	s_addc_u32 s51, s51, 0
	global_load_dword v32, v26, s[50:51] nt
	s_add_u32 s50, s50, s91
	s_addc_u32 s51, s51, 0
	global_load_dword v33, v26, s[50:51] nt
	s_add_u32 s50, s50, s91
	s_addc_u32 s51, s51, 0
	global_load_dword v34, v26, s[50:51] nt
	s_add_u32 s50, s50, s91
	s_addc_u32 s51, s51, 0
	global_load_dword v35, v26, s[50:51] nt
	s_add_u32 s50, s50, s91
	s_addc_u32 s51, s51, 0
	global_load_dword v36, v26, s[50:51] nt
	s_add_u32 s50, s50, s91
	s_addc_u32 s51, s51, 0
	global_load_dword v37, v26, s[50:51] nt
	s_add_u32 s50, s50, s91
	s_addc_u32 s51, s51, 0
	global_load_dword v38, v26, s[50:51] nt
	s_add_u32 s50, s50, s91
	s_addc_u32 s51, s51, 0
	global_load_dword v39, v26, s[50:51] nt
	s_add_u32 s50, s50, s91
	s_addc_u32 s51, s51, 0
	global_load_dword v40, v26, s[50:51] nt
	s_add_u32 s50, s50, s91
	s_addc_u32 s51, s51, 0
	global_load_dword v41, v26, s[50:51] nt
	s_add_u32 s50, s50, s91
	s_addc_u32 s51, s51, 0
	global_load_dword v42, v26, s[50:51] nt
	s_add_u32 s50, s50, s91
	s_addc_u32 s51, s51, 0
	global_load_dword v43, v26, s[50:51] nt
	s_add_u32 s50, s50, s91
	s_addc_u32 s51, s51, 0
	global_load_dword v44, v26, s[50:51] nt
	s_add_u32 s50, s50, s91
	s_addc_u32 s51, s51, 0
	global_load_dword v45, v26, s[50:51] nt
	s_waitcnt vmcnt(32)
	v_cvt_pk_bf16_f32 v46, v46, v47
	v_cvt_pk_bf16_f32 v47, v48, v49
	v_cvt_pk_bf16_f32 v48, v50, v51
	v_cvt_pk_bf16_f32 v49, v52, v53
	v_cvt_pk_bf16_f32 v50, v54, v55
	v_cvt_pk_bf16_f32 v51, v56, v57
	v_cvt_pk_bf16_f32 v52, v58, v59
	v_cvt_pk_bf16_f32 v53, v60, v61
	global_store_dwordx4 v78, v[46:49], s[56:57]
	global_store_dwordx4 v78, v[50:53], s[56:57] offset:16
	s_add_i32 s6, s6, 1
	s_cmp_ge_u32 s92, 0x80
	s_cselect_b32 s7, 28, 12
	s_cmp_ge_u32 s6, s7
	s_cbranch_scc1 .Lwf_drain2
	s_add_i32 s7, s92, 0x80
	s_and_b32 s7, s7, 0xff
	s_lshl_b32 s89, s6, 8
	s_add_i32 s89, s89, s7
	s_addk_i32 s89, 0x280
	s_lshl_b32 s7, s6, 7
	s_add_i32 s7, s7, s92
	s_addk_i32 s7, 0x800
	s_cmp_ge_u32 s6, 12
	s_cselect_b32 s89, s7, s89
	s_add_i32 s7, s89, 0xfffffe80
	s_mov_b32 s30, 2
	s_cmpk_ge_i32 s7, 0x300
	s_cselect_b32 s30, 3, s30
	s_cmpk_ge_i32 s7, 0x500
	s_cselect_b32 s30, 4, s30
	s_cmpk_ge_i32 s7, 0x700
	s_cselect_b32 s30, 5, s30
	s_cmpk_ge_i32 s7, 0x900
	s_cselect_b32 s30, 6, s30
	s_cmpk_ge_i32 s7, 0xb00
	s_cselect_b32 s30, 7, s30
	s_cmpk_ge_i32 s7, 0xd00
	s_cselect_b32 s30, 8, s30
	s_cmpk_ge_i32 s7, 0xf00
	s_cselect_b32 s30, 9, s30
	s_cmpk_ge_i32 s7, 0x1100
	s_cselect_b32 s30, 10, s30
	s_cmpk_ge_i32 s7, 0x1280
	s_cselect_b32 s30, 11, s30
	s_cmpk_ge_i32 s7, 0x1400
	s_cselect_b32 s30, 12, s30
	s_cmpk_ge_i32 s7, 0x1480
	s_cselect_b32 s30, 13, s30
	s_mul_i32 s59, s30, 48
	s_add_u32 s10, s0, s59
	s_addc_u32 s11, s1, 0
	s_load_dwordx2 s[50:51], s[10:11], 0x100
	s_load_dwordx2 s[56:57], s[10:11], 0x110
	s_load_dwordx2 s[90:91], s[10:11], 0x118
	s_load_dword s30, s[10:11], 0x128
	s_load_dwordx2 vcc, s[0:1], 0xf8
	s_waitcnt lgkmcnt(0)
	s_sub_i32 s7, s7, s30
	s_lshr_b32 s59, s90, 7
	s_add_i32 s10, s59, -1
	s_and_b32 s10, s7, s10
	s_ff1_i32_b32 s59, s59
	s_lshr_b32 s7, s7, s59
	s_lshl_b32 s10, s10, 7
	s_add_i32 s10, s10, s58
	s_lshl_b32 s11, s7, 6
	s_mul_i32 s59, s10, s91
	s_add_i32 s59, s59, s11
	s_lshl_b32 s59, s59, 2
	s_add_u32 s50, s50, s59
	s_addc_u32 s51, s51, 0
	s_mul_i32 s59, s11, s90
	s_add_i32 s59, s59, s10
	s_lshl_b32 s59, s59, 1
	s_add_u32 s56, s56, s59
	s_addc_u32 s57, s57, 0
	s_add_u32 s56, s56, vcc_lo
	s_addc_u32 s57, s57, vcc_hi
	v_mul_u32_u24_e32 v78, s90, v29
	s_lshl_b32 s91, s91, 2
	global_load_dword v46, v26, s[50:51] nt
	s_add_u32 s50, s50, s91
	s_addc_u32 s51, s51, 0
	global_load_dword v47, v26, s[50:51] nt
	s_add_u32 s50, s50, s91
	s_addc_u32 s51, s51, 0
	global_load_dword v48, v26, s[50:51] nt
	s_add_u32 s50, s50, s91
	s_addc_u32 s51, s51, 0
	global_load_dword v49, v26, s[50:51] nt
	s_add_u32 s50, s50, s91
	s_addc_u32 s51, s51, 0
	global_load_dword v50, v26, s[50:51] nt
	s_add_u32 s50, s50, s91
	s_addc_u32 s51, s51, 0
	global_load_dword v51, v26, s[50:51] nt
	s_add_u32 s50, s50, s91
	s_addc_u32 s51, s51, 0
	global_load_dword v52, v26, s[50:51] nt
	s_add_u32 s50, s50, s91
	s_addc_u32 s51, s51, 0
	global_load_dword v53, v26, s[50:51] nt
	s_add_u32 s50, s50, s91
	s_addc_u32 s51, s51, 0
	global_load_dword v54, v26, s[50:51] nt
	s_add_u32 s50, s50, s91
	s_addc_u32 s51, s51, 0
	global_load_dword v55, v26, s[50:51] nt
	s_add_u32 s50, s50, s91
	s_addc_u32 s51, s51, 0
	global_load_dword v56, v26, s[50:51] nt
	s_add_u32 s50, s50, s91
	s_addc_u32 s51, s51, 0
	global_load_dword v57, v26, s[50:51] nt
	s_add_u32 s50, s50, s91
	s_addc_u32 s51, s51, 0
	global_load_dword v58, v26, s[50:51] nt
	s_add_u32 s50, s50, s91
	s_addc_u32 s51, s51, 0
	global_load_dword v59, v26, s[50:51] nt
	s_add_u32 s50, s50, s91
	s_addc_u32 s51, s51, 0
	global_load_dword v60, v26, s[50:51] nt
	s_add_u32 s50, s50, s91
	s_addc_u32 s51, s51, 0
	global_load_dword v61, v26, s[50:51] nt
	s_branch .Lwf_loop
